# phase-7 output stores non-temporal (nt): the f32 result is never re-read
# baseline (speedup 1.0000x reference)
;     __device__ __forceinline__ void operator()(const f32x4 (&acc)[2][2][4][2], const pg8::Unit& u, int wr, int wc, int fr, int fq) const {
;         u32x4 xr[2][4][2];
; #pragma unroll
;         for (int ai = 0; ai < 2; ++ai)
; #pragma unroll
;             for (int m = 0; m < 4; ++m)
; #pragma unroll
;                 for (int bj = 0; bj < 2; ++bj)
;                     xr[ai][m][bj] = *(const u32x4*)(x2b + (size_t)(u.pm * 256 + ai * 128 + wr * 64 + m * 16 + fr) * DM + u.pn * 256 + 128 * bj + 32 * wc + 8 * fq);
;         __builtin_amdgcn_sched_barrier(0);
; #pragma unroll
;         for (int ai = 0; ai < 2; ++ai)
; #pragma unroll
;             for (int m = 0; m < 4; ++m) {
;                 const int row = u.pm * 256 + ai * 128 + wr * 64 + m * 16 + fr;
; #pragma unroll
;                 for (int bj = 0; bj < 2; ++bj) {
;                     const size_t off = (size_t)row * DM + u.pn * 256 + 128 * bj + 32 * wc + 8 * fq;
;                     const u32x4 w = xr[ai][m][bj];
;                     f32x4 ya = acc[ai][bj][m][0], yb = acc[ai][bj][m][1];
;                     ya.x += __uint_as_float(w.x << 16); ya.y += __uint_as_float(w.x & 0xffff0000u); ya.z += __uint_as_float(w.y << 16); ya.w += __uint_as_float(w.y & 0xffff0000u);
;                     yb.x += __uint_as_float(w.z << 16); yb.y += __uint_as_float(w.z & 0xffff0000u); yb.z += __uint_as_float(w.w << 16); yb.w += __uint_as_float(w.w & 0xffff0000u);
;                     *(f32x4*)(out + off) = ya; *(f32x4*)(out + off + 4) = yb;
;                 }
.LBB0_1064:
	v_lshl_add_u32 v226, s16, 8, v179
	s_lshl_b32 s18, s40, 8
	s_ashr_i32 s19, s18, 31
	v_ashrrev_i32_e32 v227, 31, v226
	v_lshl_add_u64 v[128:129], s[18:19], 1, v[176:177]
	v_lshlrev_b64 v[130:131], 11, v[226:227]
	v_or_b32_e32 v228, 16, v226
	v_lshl_add_u64 v[130:131], v[128:129], 0, v[130:131]
	v_ashrrev_i32_e32 v229, 31, v228
	global_load_dwordx4 v[202:205], v[130:131], off
	global_load_dwordx4 v[206:209], v[130:131], off offset:256
	v_lshlrev_b64 v[130:131], 11, v[228:229]
	v_or_b32_e32 v230, 32, v226
	v_lshl_add_u64 v[130:131], v[128:129], 0, v[130:131]
	v_ashrrev_i32_e32 v231, 31, v230
	global_load_dwordx4 v[210:213], v[130:131], off
	global_load_dwordx4 v[214:217], v[130:131], off offset:256
	v_lshlrev_b64 v[130:131], 11, v[230:231]
	v_or_b32_e32 v196, 48, v226
	v_lshl_add_u64 v[130:131], v[128:129], 0, v[130:131]
	v_ashrrev_i32_e32 v197, 31, v196
	global_load_dwordx4 v[218:221], v[130:131], off
	global_load_dwordx4 v[222:225], v[130:131], off offset:256
	v_lshlrev_b64 v[130:131], 11, v[196:197]
	v_add_u32_e32 v194, 0x80, v226
	v_lshl_add_u64 v[130:131], v[128:129], 0, v[130:131]
	v_ashrrev_i32_e32 v195, 31, v194
	global_load_dwordx4 v[164:167], v[130:131], off
	global_load_dwordx4 v[160:163], v[130:131], off offset:256
	v_lshlrev_b64 v[130:131], 11, v[194:195]
	v_add_u32_e32 v192, 0x90, v226
	v_lshl_add_u64 v[130:131], v[128:129], 0, v[130:131]
	v_ashrrev_i32_e32 v193, 31, v192
	global_load_dwordx4 v[156:159], v[130:131], off
	global_load_dwordx4 v[152:155], v[130:131], off offset:256
	v_lshlrev_b64 v[130:131], 11, v[192:193]
	v_add_u32_e32 v190, 0xa0, v226
	v_lshl_add_u64 v[130:131], v[128:129], 0, v[130:131]
	v_ashrrev_i32_e32 v191, 31, v190
	global_load_dwordx4 v[148:151], v[130:131], off
	global_load_dwordx4 v[144:147], v[130:131], off offset:256
	v_lshlrev_b64 v[130:131], 11, v[190:191]
	v_add_u32_e32 v188, 0xb0, v226
	v_lshl_add_u64 v[130:131], v[128:129], 0, v[130:131]
	v_ashrrev_i32_e32 v189, 31, v188
	global_load_dwordx4 v[140:143], v[130:131], off
	global_load_dwordx4 v[136:139], v[130:131], off offset:256
	v_lshlrev_b64 v[130:131], 11, v[188:189]
	v_lshl_add_u64 v[128:129], v[128:129], 0, v[130:131]
	global_load_dwordx4 v[132:135], v[128:129], off
	s_nop 0
	global_load_dwordx4 v[128:131], v[128:129], off offset:256
	s_waitcnt vmcnt(0)
	v_lshlrev_b32_e32 v234, 16, v202
	v_and_b32_e32 v235, 0xffff0000, v202
	v_lshlrev_b32_e32 v202, 16, v203
	v_and_b32_e32 v203, 0xffff0000, v203
	v_pk_add_f32 v[126:127], v[126:127], v[202:203]
	v_lshlrev_b32_e32 v202, 16, v204
	v_and_b32_e32 v203, 0xffff0000, v204
	v_pk_add_f32 v[202:203], v[120:121], v[202:203]
	v_lshlrev_b32_e32 v120, 16, v205
	v_and_b32_e32 v121, 0xffff0000, v205
	v_mov_b32_e32 v233, s19
	v_or_b32_e32 v232, s18, v178
	v_pk_add_f32 v[204:205], v[122:123], v[120:121]
	v_lshlrev_b64 v[120:121], 12, v[226:227]
	v_lshl_add_u64 v[122:123], s[76:77], 0, v[120:121]
	v_lshlrev_b64 v[120:121], 2, v[232:233]
	v_pk_add_f32 v[124:125], v[124:125], v[234:235]
	v_lshl_add_u64 v[122:123], v[122:123], 0, v[120:121]
	global_store_dwordx4 v[122:123], v[124:127], off nt
	global_store_dwordx4 v[122:123], v[202:205], off offset:16 nt
	s_andn2_b64 vcc, exec, s[0:1]
	v_lshlrev_b32_e32 v124, 16, v206
	v_and_b32_e32 v125, 0xffff0000, v206
	v_pk_add_f32 v[116:117], v[116:117], v[124:125]
	v_lshlrev_b32_e32 v124, 16, v207
	v_and_b32_e32 v125, 0xffff0000, v207
	v_pk_add_f32 v[118:119], v[118:119], v[124:125]
	v_lshlrev_b32_e32 v124, 16, v208
	v_and_b32_e32 v125, 0xffff0000, v208
	v_pk_add_f32 v[108:109], v[108:109], v[124:125]
	v_lshlrev_b32_e32 v124, 16, v209
	v_and_b32_e32 v125, 0xffff0000, v209
	v_pk_add_f32 v[110:111], v[110:111], v[124:125]
	global_store_dwordx4 v[122:123], v[116:119], off offset:512 nt
	global_store_dwordx4 v[122:123], v[108:111], off offset:528 nt
	s_mov_b64 s[0:1], -1
	s_nop 0
	v_lshlrev_b32_e32 v108, 16, v210
	v_and_b32_e32 v109, 0xffff0000, v210
	v_pk_add_f32 v[108:109], v[112:113], v[108:109]
	v_lshlrev_b32_e32 v112, 16, v212
	v_and_b32_e32 v113, 0xffff0000, v212
	v_pk_add_f32 v[104:105], v[104:105], v[112:113]
	v_lshlrev_b32_e32 v112, 16, v213
	v_and_b32_e32 v113, 0xffff0000, v213
	v_pk_add_f32 v[106:107], v[106:107], v[112:113]
	v_lshlrev_b64 v[112:113], 12, v[228:229]
	v_lshlrev_b32_e32 v110, 16, v211
	v_and_b32_e32 v111, 0xffff0000, v211
	v_lshl_add_u64 v[112:113], s[76:77], 0, v[112:113]
	v_pk_add_f32 v[110:111], v[114:115], v[110:111]
	v_lshl_add_u64 v[112:113], v[112:113], 0, v[120:121]
	global_store_dwordx4 v[112:113], v[108:111], off nt
	global_store_dwordx4 v[112:113], v[104:107], off offset:16 nt
	s_nop 1
	v_lshlrev_b32_e32 v104, 16, v214
	v_and_b32_e32 v105, 0xffff0000, v214
	v_pk_add_f32 v[100:101], v[100:101], v[104:105]
	v_lshlrev_b32_e32 v104, 16, v215
	v_and_b32_e32 v105, 0xffff0000, v215
	v_pk_add_f32 v[102:103], v[102:103], v[104:105]
	v_lshlrev_b32_e32 v104, 16, v216
	v_and_b32_e32 v105, 0xffff0000, v216
	v_pk_add_f32 v[92:93], v[92:93], v[104:105]
	v_lshlrev_b32_e32 v104, 16, v217
	v_and_b32_e32 v105, 0xffff0000, v217
	v_pk_add_f32 v[94:95], v[94:95], v[104:105]
	global_store_dwordx4 v[112:113], v[100:103], off offset:512 nt
	global_store_dwordx4 v[112:113], v[92:95], off offset:528 nt
	s_nop 1
	v_lshlrev_b32_e32 v92, 16, v218
	v_and_b32_e32 v93, 0xffff0000, v218
	v_pk_add_f32 v[92:93], v[96:97], v[92:93]
	v_lshlrev_b32_e32 v96, 16, v220
	v_and_b32_e32 v97, 0xffff0000, v220
	v_pk_add_f32 v[88:89], v[88:89], v[96:97]
	v_lshlrev_b32_e32 v96, 16, v221
	v_and_b32_e32 v97, 0xffff0000, v221
	v_pk_add_f32 v[90:91], v[90:91], v[96:97]
	v_lshlrev_b64 v[96:97], 12, v[230:231]
	v_lshlrev_b32_e32 v94, 16, v219
	v_and_b32_e32 v95, 0xffff0000, v219
;     __device__ __forceinline__ void operator()(const f32x4 (&acc)[2][2][4][2], const pg8::Unit& u, int wr, int wc, int fr, int fq) const {
;     ...
;                 for (int bj = 0; bj < 2; ++bj) {
;                     const size_t off = (size_t)row * DM + u.pn * 256 + 128 * bj + 32 * wc + 8 * fq;
;                     const u32x4 w = xr[ai][m][bj];
;                     f32x4 ya = acc[ai][bj][m][0], yb = acc[ai][bj][m][1];
;                     ya.x += __uint_as_float(w.x << 16); ya.y += __uint_as_float(w.x & 0xffff0000u); ya.z += __uint_as_float(w.y << 16); ya.w += __uint_as_float(w.y & 0xffff0000u);
;                     yb.x += __uint_as_float(w.z << 16); yb.y += __uint_as_float(w.z & 0xffff0000u); yb.z += __uint_as_float(w.w << 16); yb.w += __uint_as_float(w.w & 0xffff0000u);
;                     *(f32x4*)(out + off) = ya; *(f32x4*)(out + off + 4) = yb;
	v_lshl_add_u64 v[96:97], s[76:77], 0, v[96:97]
	v_pk_add_f32 v[94:95], v[98:99], v[94:95]
	v_lshl_add_u64 v[96:97], v[96:97], 0, v[120:121]
	global_store_dwordx4 v[96:97], v[92:95], off nt
	global_store_dwordx4 v[96:97], v[88:91], off offset:16 nt
	s_nop 1
	v_lshlrev_b32_e32 v88, 16, v222
	v_and_b32_e32 v89, 0xffff0000, v222
	v_pk_add_f32 v[84:85], v[84:85], v[88:89]
	v_lshlrev_b32_e32 v88, 16, v223
	v_and_b32_e32 v89, 0xffff0000, v223
	v_pk_add_f32 v[86:87], v[86:87], v[88:89]
	v_lshlrev_b32_e32 v88, 16, v224
	v_and_b32_e32 v89, 0xffff0000, v224
	v_pk_add_f32 v[76:77], v[76:77], v[88:89]
	v_lshlrev_b32_e32 v88, 16, v225
	v_and_b32_e32 v89, 0xffff0000, v225
	v_pk_add_f32 v[78:79], v[78:79], v[88:89]
	global_store_dwordx4 v[96:97], v[84:87], off offset:512 nt
	global_store_dwordx4 v[96:97], v[76:79], off offset:528 nt
	s_nop 1
	v_lshlrev_b32_e32 v76, 16, v164
	v_and_b32_e32 v77, 0xffff0000, v164
	v_pk_add_f32 v[76:77], v[80:81], v[76:77]
	v_lshlrev_b32_e32 v80, 16, v166
	v_and_b32_e32 v81, 0xffff0000, v166
	v_pk_add_f32 v[72:73], v[72:73], v[80:81]
	v_lshlrev_b32_e32 v80, 16, v167
	v_and_b32_e32 v81, 0xffff0000, v167
	v_pk_add_f32 v[74:75], v[74:75], v[80:81]
	v_lshlrev_b64 v[80:81], 12, v[196:197]
	v_lshlrev_b32_e32 v78, 16, v165
	v_and_b32_e32 v79, 0xffff0000, v165
	v_lshl_add_u64 v[80:81], s[76:77], 0, v[80:81]
	v_pk_add_f32 v[78:79], v[82:83], v[78:79]
	v_lshl_add_u64 v[80:81], v[80:81], 0, v[120:121]
	global_store_dwordx4 v[80:81], v[76:79], off nt
	global_store_dwordx4 v[80:81], v[72:75], off offset:16 nt
	s_nop 1
	v_lshlrev_b32_e32 v72, 16, v160
	v_and_b32_e32 v73, 0xffff0000, v160
	v_pk_add_f32 v[68:69], v[68:69], v[72:73]
	v_lshlrev_b32_e32 v72, 16, v161
	v_and_b32_e32 v73, 0xffff0000, v161
	v_pk_add_f32 v[70:71], v[70:71], v[72:73]
	v_lshlrev_b32_e32 v72, 16, v162
	v_and_b32_e32 v73, 0xffff0000, v162
	v_pk_add_f32 v[64:65], v[64:65], v[72:73]
	v_lshlrev_b32_e32 v72, 16, v163
	v_and_b32_e32 v73, 0xffff0000, v163
	v_pk_add_f32 v[66:67], v[66:67], v[72:73]
	global_store_dwordx4 v[80:81], v[68:71], off offset:512 nt
	global_store_dwordx4 v[80:81], v[64:67], off offset:528 nt
	s_nop 1
	v_lshlrev_b32_e32 v64, 16, v156
	v_and_b32_e32 v65, 0xffff0000, v156
	v_pk_add_f32 v[60:61], v[60:61], v[64:65]
	v_lshlrev_b32_e32 v64, 16, v157
	v_and_b32_e32 v65, 0xffff0000, v157
	v_pk_add_f32 v[62:63], v[62:63], v[64:65]
	v_lshlrev_b32_e32 v64, 16, v158
	v_and_b32_e32 v65, 0xffff0000, v158
	v_pk_add_f32 v[56:57], v[56:57], v[64:65]
	v_lshlrev_b32_e32 v64, 16, v159
	v_and_b32_e32 v65, 0xffff0000, v159
	v_pk_add_f32 v[58:59], v[58:59], v[64:65]
	v_lshlrev_b64 v[64:65], 12, v[194:195]
	v_lshl_add_u64 v[64:65], s[76:77], 0, v[64:65]
	v_lshl_add_u64 v[64:65], v[64:65], 0, v[120:121]
	global_store_dwordx4 v[64:65], v[60:63], off nt
	global_store_dwordx4 v[64:65], v[56:59], off offset:16 nt
	s_nop 1
	v_lshlrev_b32_e32 v56, 16, v152
	v_and_b32_e32 v57, 0xffff0000, v152
	v_pk_add_f32 v[52:53], v[52:53], v[56:57]
	v_lshlrev_b32_e32 v56, 16, v153
	v_and_b32_e32 v57, 0xffff0000, v153
	v_pk_add_f32 v[54:55], v[54:55], v[56:57]
	v_lshlrev_b32_e32 v56, 16, v154
	v_and_b32_e32 v57, 0xffff0000, v154
	v_pk_add_f32 v[44:45], v[44:45], v[56:57]
	v_lshlrev_b32_e32 v56, 16, v155
	v_and_b32_e32 v57, 0xffff0000, v155
	v_pk_add_f32 v[46:47], v[46:47], v[56:57]
	global_store_dwordx4 v[64:65], v[52:55], off offset:512 nt
	global_store_dwordx4 v[64:65], v[44:47], off offset:528 nt
	s_nop 1
	v_lshlrev_b32_e32 v44, 16, v148
	v_and_b32_e32 v45, 0xffff0000, v148
	v_pk_add_f32 v[44:45], v[48:49], v[44:45]
	v_lshlrev_b32_e32 v48, 16, v150
	v_and_b32_e32 v49, 0xffff0000, v150
	v_pk_add_f32 v[40:41], v[40:41], v[48:49]
	v_lshlrev_b32_e32 v48, 16, v151
;     __device__ __forceinline__ void operator()(const f32x4 (&acc)[2][2][4][2], const pg8::Unit& u, int wr, int wc, int fr, int fq) const {
;     ...
;                 for (int bj = 0; bj < 2; ++bj) {
;                     const size_t off = (size_t)row * DM + u.pn * 256 + 128 * bj + 32 * wc + 8 * fq;
;                     const u32x4 w = xr[ai][m][bj];
;                     f32x4 ya = acc[ai][bj][m][0], yb = acc[ai][bj][m][1];
;                     ya.x += __uint_as_float(w.x << 16); ya.y += __uint_as_float(w.x & 0xffff0000u); ya.z += __uint_as_float(w.y << 16); ya.w += __uint_as_float(w.y & 0xffff0000u);
;                     yb.x += __uint_as_float(w.z << 16); yb.y += __uint_as_float(w.z & 0xffff0000u); yb.z += __uint_as_float(w.w << 16); yb.w += __uint_as_float(w.w & 0xffff0000u);
;                     *(f32x4*)(out + off) = ya; *(f32x4*)(out + off + 4) = yb;
;                 }
;             }
	v_and_b32_e32 v49, 0xffff0000, v151
	v_pk_add_f32 v[42:43], v[42:43], v[48:49]
	v_lshlrev_b64 v[48:49], 12, v[192:193]
	v_lshlrev_b32_e32 v46, 16, v149
	v_and_b32_e32 v47, 0xffff0000, v149
	v_lshl_add_u64 v[48:49], s[76:77], 0, v[48:49]
	v_pk_add_f32 v[46:47], v[50:51], v[46:47]
	v_lshl_add_u64 v[48:49], v[48:49], 0, v[120:121]
	global_store_dwordx4 v[48:49], v[44:47], off nt
	global_store_dwordx4 v[48:49], v[40:43], off offset:16 nt
	s_nop 1
	v_lshlrev_b32_e32 v40, 16, v144
	v_and_b32_e32 v41, 0xffff0000, v144
	v_pk_add_f32 v[36:37], v[36:37], v[40:41]
	v_lshlrev_b32_e32 v40, 16, v145
	v_and_b32_e32 v41, 0xffff0000, v145
	v_pk_add_f32 v[38:39], v[38:39], v[40:41]
	v_lshlrev_b32_e32 v40, 16, v146
	v_and_b32_e32 v41, 0xffff0000, v146
	v_pk_add_f32 v[28:29], v[28:29], v[40:41]
	v_lshlrev_b32_e32 v40, 16, v147
	v_and_b32_e32 v41, 0xffff0000, v147
	v_pk_add_f32 v[30:31], v[30:31], v[40:41]
	global_store_dwordx4 v[48:49], v[36:39], off offset:512 nt
	global_store_dwordx4 v[48:49], v[28:31], off offset:528 nt
	s_nop 1
	v_lshlrev_b32_e32 v28, 16, v140
	v_and_b32_e32 v29, 0xffff0000, v140
	v_pk_add_f32 v[28:29], v[32:33], v[28:29]
	v_lshlrev_b32_e32 v32, 16, v142
	v_and_b32_e32 v33, 0xffff0000, v142
	v_pk_add_f32 v[24:25], v[24:25], v[32:33]
	v_lshlrev_b32_e32 v32, 16, v143
	v_and_b32_e32 v33, 0xffff0000, v143
	v_pk_add_f32 v[26:27], v[26:27], v[32:33]
	v_lshlrev_b64 v[32:33], 12, v[190:191]
	v_lshlrev_b32_e32 v30, 16, v141
	v_and_b32_e32 v31, 0xffff0000, v141
	v_lshl_add_u64 v[32:33], s[76:77], 0, v[32:33]
	v_pk_add_f32 v[30:31], v[34:35], v[30:31]
	v_lshl_add_u64 v[32:33], v[32:33], 0, v[120:121]
	global_store_dwordx4 v[32:33], v[28:31], off nt
	global_store_dwordx4 v[32:33], v[24:27], off offset:16 nt
	s_nop 1
	v_lshlrev_b32_e32 v24, 16, v136
	v_and_b32_e32 v25, 0xffff0000, v136
	v_pk_add_f32 v[20:21], v[20:21], v[24:25]
	v_lshlrev_b32_e32 v24, 16, v137
	v_and_b32_e32 v25, 0xffff0000, v137
	v_pk_add_f32 v[22:23], v[22:23], v[24:25]
	v_lshlrev_b32_e32 v24, 16, v138
	v_and_b32_e32 v25, 0xffff0000, v138
	v_pk_add_f32 v[12:13], v[12:13], v[24:25]
	v_lshlrev_b32_e32 v24, 16, v139
	v_and_b32_e32 v25, 0xffff0000, v139
	v_pk_add_f32 v[14:15], v[14:15], v[24:25]
	global_store_dwordx4 v[32:33], v[20:23], off offset:512 nt
	global_store_dwordx4 v[32:33], v[12:15], off offset:528 nt
	s_nop 1
	v_lshlrev_b32_e32 v12, 16, v132
	v_and_b32_e32 v13, 0xffff0000, v132
	v_pk_add_f32 v[12:13], v[16:17], v[12:13]
	v_lshlrev_b32_e32 v16, 16, v134
	v_and_b32_e32 v17, 0xffff0000, v134
	v_pk_add_f32 v[8:9], v[8:9], v[16:17]
	v_lshlrev_b32_e32 v16, 16, v135
	v_and_b32_e32 v17, 0xffff0000, v135
	v_pk_add_f32 v[10:11], v[10:11], v[16:17]
	v_lshlrev_b64 v[16:17], 12, v[188:189]
	v_lshlrev_b32_e32 v14, 16, v133
	v_and_b32_e32 v15, 0xffff0000, v133
	v_lshl_add_u64 v[16:17], s[76:77], 0, v[16:17]
	v_pk_add_f32 v[14:15], v[18:19], v[14:15]
	v_lshl_add_u64 v[16:17], v[16:17], 0, v[120:121]
	global_store_dwordx4 v[16:17], v[12:15], off nt
	global_store_dwordx4 v[16:17], v[8:11], off offset:16 nt
	s_nop 1
	v_lshlrev_b32_e32 v8, 16, v128
	v_and_b32_e32 v9, 0xffff0000, v128
	v_pk_add_f32 v[4:5], v[4:5], v[8:9]
	v_lshlrev_b32_e32 v8, 16, v129
	v_and_b32_e32 v9, 0xffff0000, v129
	v_pk_add_f32 v[6:7], v[6:7], v[8:9]
	v_lshlrev_b32_e32 v8, 16, v130
	v_and_b32_e32 v9, 0xffff0000, v130
	v_pk_add_f32 v[0:1], v[0:1], v[8:9]
	v_lshlrev_b32_e32 v8, 16, v131
	v_and_b32_e32 v9, 0xffff0000, v131
	v_pk_add_f32 v[2:3], v[2:3], v[8:9]
	global_store_dwordx4 v[16:17], v[4:7], off offset:512 nt
	global_store_dwordx4 v[16:17], v[0:3], off offset:528 nt
	s_cbranch_vccnz .LBB0_1053
	s_andn2_b64 vcc, exec, s[2:3]
	s_cbranch_vccnz .LBB0_1052
	s_barrier
	s_branch .LBB0_1052
